# P4 group norm: 64-lane sum reductions done in registers (DPP quad_perm/row_half_mirror/row_mirror adds + permlane16/32 swaps) instead of six ds_bpermute LDS round trips each
# baseline (speedup 1.0000x reference)
.LBB0_744:
	v_lshl_add_u64 v[4:5], v[2:3], 0, s[30:31]
	v_add_co_u32_e32 v6, vcc, 0x10800000, v4
	v_lshl_add_u64 v[8:9], v[0:1], 0, s[30:31]
	s_nop 0
	v_addc_co_u32_e32 v7, vcc, 0, v5, vcc
	v_add_co_u32_e32 v32, vcc, 0x18800000, v8
	flat_load_dwordx2 v[26:27], v[6:7]
	s_nop 0
	v_addc_co_u32_e32 v33, vcc, 0, v9, vcc
	flat_load_dwordx2 v[38:39], v[32:33]
	flat_load_dwordx2 v[40:41], v[6:7] offset:2048
	flat_load_dwordx2 v[42:43], v[32:33] offset:2048
	v_add_co_u32_e32 v6, vcc, 0x10801000, v4
	s_mov_b32 s20, 0x358637bd
	s_nop 0
	v_addc_co_u32_e32 v7, vcc, 0, v5, vcc
	v_add_co_u32_e32 v20, vcc, 0x18801000, v8
	flat_load_dwordx2 v[34:35], v[6:7]
	s_nop 0
	v_addc_co_u32_e32 v21, vcc, 0, v9, vcc
	flat_load_dwordx2 v[36:37], v[20:21]
	flat_load_dwordx2 v[30:31], v[6:7] offset:2048
	flat_load_dwordx2 v[28:29], v[20:21] offset:2048
	v_add_co_u32_e32 v6, vcc, 0x10802000, v4
	s_add_u32 s30, s30, 0x4000
	s_nop 0
	v_addc_co_u32_e32 v7, vcc, 0, v5, vcc
	v_add_co_u32_e32 v10, vcc, 0x18802000, v8
	flat_load_dwordx2 v[22:23], v[6:7]
	s_nop 0
	v_addc_co_u32_e32 v11, vcc, 0, v9, vcc
	flat_load_dwordx2 v[24:25], v[10:11]
	flat_load_dwordx2 v[18:19], v[6:7] offset:2048
	flat_load_dwordx2 v[16:17], v[10:11] offset:2048
	v_add_co_u32_e32 v6, vcc, 0x10803000, v4
	s_addc_u32 s31, s31, 0
	s_nop 0
	v_addc_co_u32_e32 v7, vcc, 0, v5, vcc
	v_add_co_u32_e32 v4, vcc, 0x18803000, v8
	flat_load_dwordx2 v[12:13], v[6:7]
	s_nop 0
	v_addc_co_u32_e32 v5, vcc, 0, v9, vcc
	flat_load_dwordx2 v[14:15], v[4:5]
	flat_load_dwordx2 v[8:9], v[6:7] offset:2048
	s_nop 0
	flat_load_dwordx2 v[6:7], v[4:5] offset:2048
	s_cmp_lg_u32 s30, 0x10000
	s_waitcnt vmcnt(0) lgkmcnt(0)
	v_and_b32_e32 v45, 0xffff0000, v27
	v_and_b32_e32 v47, 0xffff0000, v39
	v_lshlrev_b32_e32 v46, 16, v39
	v_and_b32_e32 v39, 0xffff0000, v38
	v_lshlrev_b32_e32 v38, 16, v38
	v_mul_f32_e32 v52, 0xbfb8aa3b, v46
	v_mul_f32_e32 v53, 0xbfb8aa3b, v47
	v_and_b32_e32 v55, 0xffff0000, v43
	v_lshlrev_b32_e32 v54, 16, v43
	v_and_b32_e32 v43, 0xffff0000, v42
	v_lshlrev_b32_e32 v42, 16, v42
	v_mul_f32_e32 v48, 0xbfb8aa3b, v38
	v_mul_f32_e32 v49, 0xbfb8aa3b, v39
	v_exp_f32_e32 v52, v52
	v_exp_f32_e32 v53, v53
	v_mul_f32_e32 v56, 0xbfb8aa3b, v42
	v_mul_f32_e32 v57, 0xbfb8aa3b, v43
	v_exp_f32_e32 v48, v48
	v_exp_f32_e32 v49, v49
	v_exp_f32_e32 v56, v56
	v_exp_f32_e32 v57, v57
	v_add_f32_e32 v52, 1.0, v52
	v_add_f32_e32 v53, 1.0, v53
	v_add_f32_e32 v48, 1.0, v48
	v_add_f32_e32 v49, 1.0, v49
	v_rcp_f32_e32 v52, v52
	v_rcp_f32_e32 v53, v53
	v_add_f32_e32 v56, 1.0, v56
	v_add_f32_e32 v57, 1.0, v57
	v_rcp_f32_e32 v48, v48
	v_rcp_f32_e32 v49, v49
	v_rcp_f32_e32 v56, v56
	v_rcp_f32_e32 v57, v57
	v_lshlrev_b32_e32 v44, 16, v27
	v_and_b32_e32 v27, 0xffff0000, v26
	v_lshlrev_b32_e32 v26, 16, v26
	v_pk_mul_f32 v[46:47], v[52:53], v[46:47]
	v_and_b32_e32 v53, 0xffff0000, v41
	v_lshlrev_b32_e32 v52, 16, v41
	v_and_b32_e32 v41, 0xffff0000, v40
	v_lshlrev_b32_e32 v40, 16, v40
	v_pk_mul_f32 v[38:39], v[48:49], v[38:39]
	v_add_f32_e32 v48, v27, v26
	v_pk_mul_f32 v[42:43], v[56:57], v[42:43]
	v_add_f32_e32 v56, v41, v40
	v_add_f32_e32 v48, v48, v44
	v_add_f32_e32 v56, v56, v52
	v_add_f32_e32 v48, v48, v45
	v_add_f32_e32 v56, v56, v53
	s_nop 1
	v_add_f32_dpp v48, v48, v48 quad_perm:[1,0,3,2] row_mask:0xf bank_mask:0xf
	v_add_f32_dpp v56, v56, v56 quad_perm:[1,0,3,2] row_mask:0xf bank_mask:0xf
	s_nop 1
	v_add_f32_dpp v48, v48, v48 quad_perm:[2,3,0,1] row_mask:0xf bank_mask:0xf
	v_add_f32_dpp v56, v56, v56 quad_perm:[2,3,0,1] row_mask:0xf bank_mask:0xf
	s_nop 1
	v_add_f32_dpp v48, v48, v48 row_half_mirror row_mask:0xf bank_mask:0xf
	v_add_f32_dpp v56, v56, v56 row_half_mirror row_mask:0xf bank_mask:0xf
	s_nop 1
	v_add_f32_dpp v48, v48, v48 row_mirror row_mask:0xf bank_mask:0xf
	v_add_f32_dpp v56, v56, v56 row_mirror row_mask:0xf bank_mask:0xf
	v_mov_b32_e32 v49, v48
	v_mov_b32_e32 v57, v56
	s_nop 1
	v_permlane16_swap_b32_e32 v48, v49
	v_permlane16_swap_b32_e32 v56, v57
	v_add_f32_e32 v48, v48, v49
	v_add_f32_e32 v56, v56, v57
	v_mov_b32_e32 v49, v48
	v_mov_b32_e32 v57, v56
	s_nop 1
	v_permlane32_swap_b32_e32 v48, v49
	v_permlane32_swap_b32_e32 v56, v57
	v_add_f32_e32 v48, v48, v49
	v_add_f32_e32 v56, v56, v57
	v_mul_f32_e32 v48, 0x3b800000, v48
	v_mul_f32_e32 v56, 0x3b800000, v56
	v_pk_add_f32 v[50:51], v[26:27], v[48:49] op_sel_hi:[1,0] neg_lo:[0,1] neg_hi:[0,1]
	v_pk_add_f32 v[40:41], v[40:41], v[56:57] op_sel_hi:[1,0] neg_lo:[0,1] neg_hi:[0,1]
	v_pk_add_f32 v[44:45], v[44:45], v[48:49] op_sel_hi:[1,0] neg_lo:[0,1] neg_hi:[0,1]
	v_pk_mul_f32 v[26:27], v[50:51], v[50:51]
	v_pk_add_f32 v[52:53], v[52:53], v[56:57] op_sel_hi:[1,0] neg_lo:[0,1] neg_hi:[0,1]
	v_pk_mul_f32 v[56:57], v[40:41], v[40:41]
	v_pk_mul_f32 v[48:49], v[44:45], v[44:45]
	v_pk_mul_f32 v[58:59], v[52:53], v[52:53]
	v_mov_b32_e32 v60, v56
	v_mov_b32_e32 v61, v26
	v_mov_b32_e32 v26, v57
	v_pk_add_f32 v[26:27], v[60:61], v[26:27]
	v_mov_b32_e32 v56, v58
	v_mov_b32_e32 v57, v48
	v_pk_add_f32 v[26:27], v[56:57], v[26:27]
	v_mov_b32_e32 v48, v59
	v_pk_add_f32 v[26:27], v[48:49], v[26:27]
	s_nop 1
	v_add_f32_dpp v26, v26, v26 quad_perm:[1,0,3,2] row_mask:0xf bank_mask:0xf
	v_add_f32_dpp v27, v27, v27 quad_perm:[1,0,3,2] row_mask:0xf bank_mask:0xf
	s_nop 1
	v_add_f32_dpp v26, v26, v26 quad_perm:[2,3,0,1] row_mask:0xf bank_mask:0xf
	v_add_f32_dpp v27, v27, v27 quad_perm:[2,3,0,1] row_mask:0xf bank_mask:0xf
	s_nop 1
	v_add_f32_dpp v26, v26, v26 row_half_mirror row_mask:0xf bank_mask:0xf
	v_add_f32_dpp v27, v27, v27 row_half_mirror row_mask:0xf bank_mask:0xf
	s_nop 1
	v_add_f32_dpp v26, v26, v26 row_mirror row_mask:0xf bank_mask:0xf
	v_add_f32_dpp v27, v27, v27 row_mirror row_mask:0xf bank_mask:0xf
	v_mov_b32_e32 v48, v26
	v_mov_b32_e32 v49, v27
	s_nop 1
	v_permlane16_swap_b32_e32 v26, v48
	v_permlane16_swap_b32_e32 v27, v49
	v_add_f32_e32 v26, v26, v48
	v_add_f32_e32 v27, v27, v49
	v_mov_b32_e32 v48, v26
	v_mov_b32_e32 v49, v27
	s_nop 1
	v_permlane32_swap_b32_e32 v26, v48
	v_permlane32_swap_b32_e32 v27, v49
	v_add_f32_e32 v48, v26, v48
	v_add_f32_e32 v49, v27, v49
	v_mov_b64_e32 v[26:27], s[20:21]
	v_pk_fma_f32 v[48:49], v[48:49], s[28:29], v[26:27] op_sel_hi:[1,0,0]
	s_nop 0
	v_mul_f32_e32 v56, 0x4b800000, v49
	v_cmp_gt_f32_e32 vcc, s39, v49
	v_cmp_gt_f32_e64 s[20:21], s39, v48
	s_nop 0
	v_cndmask_b32_e32 v49, v49, v56, vcc
	v_rsq_f32_e32 v49, v49
	s_nop 0
	v_mul_f32_e32 v56, 0x45800000, v49
	v_cndmask_b32_e32 v56, v49, v56, vcc
	v_pk_mul_f32 v[50:51], v[50:51], v[56:57] op_sel_hi:[1,0]
	v_pk_mul_f32 v[44:45], v[44:45], v[56:57] op_sel_hi:[1,0]
	v_pk_mul_f32 v[38:39], v[38:39], v[50:51]
	v_pk_mul_f32 v[44:45], v[46:47], v[44:45]
	v_cvt_pk_bf16_f32 v38, v38, v39
	v_cvt_pk_bf16_f32 v39, v44, v45
	flat_store_dwordx2 v[32:33], v[38:39]
	v_mul_f32_e32 v38, 0x4b800000, v48
	v_cndmask_b32_e64 v38, v48, v38, s[20:21]
	v_rsq_f32_e32 v38, v38
	v_and_b32_e32 v47, 0xffff0000, v29
	v_lshlrev_b32_e32 v46, 16, v29
	v_and_b32_e32 v29, 0xffff0000, v28
	v_mul_f32_e32 v39, 0x45800000, v38
	v_cndmask_b32_e64 v38, v38, v39, s[20:21]
	v_pk_mul_f32 v[40:41], v[40:41], v[38:39] op_sel_hi:[1,0]
	v_mul_f32_e32 v39, 0xbfb8aa3b, v54
	v_pk_mul_f32 v[40:41], v[42:43], v[40:41]
	v_mul_f32_e32 v43, 0xbfb8aa3b, v55
	v_exp_f32_e32 v39, v39
	v_exp_f32_e32 v43, v43
	v_cvt_pk_bf16_f32 v40, v40, v41
	v_lshlrev_b32_e32 v28, 16, v28
	v_add_f32_e32 v39, 1.0, v39
	v_add_f32_e32 v43, 1.0, v43
	v_rcp_f32_e32 v42, v39
	v_rcp_f32_e32 v43, v43
	v_pk_mul_f32 v[38:39], v[52:53], v[38:39] op_sel_hi:[1,0]
	v_mul_f32_e32 v48, 0xbfb8aa3b, v28
	v_mul_f32_e32 v49, 0xbfb8aa3b, v29
	v_pk_mul_f32 v[42:43], v[42:43], v[54:55]
	v_exp_f32_e32 v48, v48
	v_pk_mul_f32 v[38:39], v[42:43], v[38:39]
	v_exp_f32_e32 v49, v49
	v_cvt_pk_bf16_f32 v41, v38, v39
	v_and_b32_e32 v39, 0xffff0000, v37
	v_lshlrev_b32_e32 v38, 16, v37
	v_and_b32_e32 v37, 0xffff0000, v36
	v_lshlrev_b32_e32 v36, 16, v36
	v_mul_f32_e32 v44, 0xbfb8aa3b, v38
	v_mul_f32_e32 v45, 0xbfb8aa3b, v39
	flat_store_dwordx2 v[32:33], v[40:41] offset:2048
	v_mul_f32_e32 v40, 0xbfb8aa3b, v36
	v_mul_f32_e32 v41, 0xbfb8aa3b, v37
	v_exp_f32_e32 v44, v44
	v_exp_f32_e32 v45, v45
	v_exp_f32_e32 v40, v40
	v_exp_f32_e32 v41, v41
	v_add_f32_e32 v44, 1.0, v44
	v_add_f32_e32 v45, 1.0, v45
	v_add_f32_e32 v40, 1.0, v40
	v_add_f32_e32 v41, 1.0, v41
	v_rcp_f32_e32 v44, v44
	v_rcp_f32_e32 v45, v45
	v_add_f32_e32 v48, 1.0, v48
	v_add_f32_e32 v49, 1.0, v49
	v_rcp_f32_e32 v40, v40
	v_rcp_f32_e32 v41, v41
	v_rcp_f32_e32 v48, v48
	v_rcp_f32_e32 v49, v49
	v_and_b32_e32 v33, 0xffff0000, v35
	v_lshlrev_b32_e32 v32, 16, v35
	v_and_b32_e32 v35, 0xffff0000, v34
	v_lshlrev_b32_e32 v34, 16, v34
	v_pk_mul_f32 v[38:39], v[44:45], v[38:39]
	v_and_b32_e32 v45, 0xffff0000, v31
	v_lshlrev_b32_e32 v44, 16, v31
	v_and_b32_e32 v31, 0xffff0000, v30
	v_lshlrev_b32_e32 v30, 16, v30
	v_pk_mul_f32 v[36:37], v[40:41], v[36:37]
	v_add_f32_e32 v40, v35, v34
	v_pk_mul_f32 v[28:29], v[48:49], v[28:29]
	v_add_f32_e32 v48, v31, v30
	v_add_f32_e32 v40, v40, v32
	v_add_f32_e32 v48, v48, v44
	v_add_f32_e32 v40, v40, v33
	v_add_f32_e32 v48, v48, v45
	s_nop 1
	v_add_f32_dpp v40, v40, v40 quad_perm:[1,0,3,2] row_mask:0xf bank_mask:0xf
	v_add_f32_dpp v48, v48, v48 quad_perm:[1,0,3,2] row_mask:0xf bank_mask:0xf
	s_nop 1
	v_add_f32_dpp v40, v40, v40 quad_perm:[2,3,0,1] row_mask:0xf bank_mask:0xf
	v_add_f32_dpp v48, v48, v48 quad_perm:[2,3,0,1] row_mask:0xf bank_mask:0xf
	s_nop 1
	v_add_f32_dpp v40, v40, v40 row_half_mirror row_mask:0xf bank_mask:0xf
	v_add_f32_dpp v48, v48, v48 row_half_mirror row_mask:0xf bank_mask:0xf
	s_nop 1
	v_add_f32_dpp v40, v40, v40 row_mirror row_mask:0xf bank_mask:0xf
	v_add_f32_dpp v48, v48, v48 row_mirror row_mask:0xf bank_mask:0xf
	v_mov_b32_e32 v41, v40
	v_mov_b32_e32 v49, v48
	s_nop 1
	v_permlane16_swap_b32_e32 v40, v41
	v_permlane16_swap_b32_e32 v48, v49
	v_add_f32_e32 v40, v40, v41
	v_add_f32_e32 v48, v48, v49
	v_mov_b32_e32 v41, v40
	v_mov_b32_e32 v49, v48
	s_nop 1
	v_permlane32_swap_b32_e32 v40, v41
	v_permlane32_swap_b32_e32 v48, v49
	v_add_f32_e32 v40, v40, v41
	v_add_f32_e32 v48, v48, v49
	v_mul_f32_e32 v40, 0x3b800000, v40
	v_mul_f32_e32 v48, 0x3b800000, v48
	v_pk_add_f32 v[34:35], v[34:35], v[40:41] op_sel_hi:[1,0] neg_lo:[0,1] neg_hi:[0,1]
	v_pk_add_f32 v[30:31], v[30:31], v[48:49] op_sel_hi:[1,0] neg_lo:[0,1] neg_hi:[0,1]
	v_pk_add_f32 v[32:33], v[32:33], v[40:41] op_sel_hi:[1,0] neg_lo:[0,1] neg_hi:[0,1]
	v_pk_mul_f32 v[40:41], v[34:35], v[34:35]
	v_pk_add_f32 v[44:45], v[44:45], v[48:49] op_sel_hi:[1,0] neg_lo:[0,1] neg_hi:[0,1]
	v_pk_mul_f32 v[48:49], v[30:31], v[30:31]
	v_pk_mul_f32 v[42:43], v[32:33], v[32:33]
	v_pk_mul_f32 v[50:51], v[44:45], v[44:45]
	v_mov_b32_e32 v52, v48
	v_mov_b32_e32 v53, v40
	v_mov_b32_e32 v40, v49
	v_pk_add_f32 v[40:41], v[52:53], v[40:41]
	v_mov_b32_e32 v48, v50
	v_mov_b32_e32 v49, v42
	v_pk_add_f32 v[40:41], v[48:49], v[40:41]
	v_mov_b32_e32 v42, v51
	v_pk_add_f32 v[40:41], v[42:43], v[40:41]
	s_nop 1
	v_add_f32_dpp v40, v40, v40 quad_perm:[1,0,3,2] row_mask:0xf bank_mask:0xf
	v_add_f32_dpp v41, v41, v41 quad_perm:[1,0,3,2] row_mask:0xf bank_mask:0xf
	s_nop 1
	v_add_f32_dpp v40, v40, v40 quad_perm:[2,3,0,1] row_mask:0xf bank_mask:0xf
	v_add_f32_dpp v41, v41, v41 quad_perm:[2,3,0,1] row_mask:0xf bank_mask:0xf
	s_nop 1
	v_add_f32_dpp v40, v40, v40 row_half_mirror row_mask:0xf bank_mask:0xf
	v_add_f32_dpp v41, v41, v41 row_half_mirror row_mask:0xf bank_mask:0xf
	s_nop 1
	v_add_f32_dpp v40, v40, v40 row_mirror row_mask:0xf bank_mask:0xf
	v_add_f32_dpp v41, v41, v41 row_mirror row_mask:0xf bank_mask:0xf
	v_mov_b32_e32 v42, v40
	v_mov_b32_e32 v43, v41
	s_nop 1
	v_permlane16_swap_b32_e32 v40, v42
	v_permlane16_swap_b32_e32 v41, v43
	v_add_f32_e32 v40, v40, v42
	v_add_f32_e32 v41, v41, v43
	v_mov_b32_e32 v42, v40
	v_mov_b32_e32 v43, v41
	s_nop 1
	v_permlane32_swap_b32_e32 v40, v42
	v_permlane32_swap_b32_e32 v41, v43
	v_add_f32_e32 v40, v40, v42
	v_add_f32_e32 v41, v41, v43
	s_nop 0
	v_pk_fma_f32 v[40:41], v[40:41], s[28:29], v[26:27] op_sel_hi:[1,0,0]
	s_nop 0
	v_mul_f32_e32 v42, 0x4b800000, v41
	v_cmp_gt_f32_e64 s[20:21], s39, v41
	v_cmp_gt_f32_e32 vcc, s39, v40
	s_nop 0
	v_cndmask_b32_e64 v41, v41, v42, s[20:21]
	v_rsq_f32_e32 v41, v41
	s_nop 0
	v_mul_f32_e32 v42, 0x45800000, v41
	v_cndmask_b32_e64 v42, v41, v42, s[20:21]
	v_pk_mul_f32 v[34:35], v[34:35], v[42:43] op_sel_hi:[1,0]
	v_pk_mul_f32 v[32:33], v[32:33], v[42:43] op_sel_hi:[1,0]
	v_pk_mul_f32 v[34:35], v[36:37], v[34:35]
	v_pk_mul_f32 v[32:33], v[38:39], v[32:33]
	v_cvt_pk_bf16_f32 v34, v34, v35
	v_cvt_pk_bf16_f32 v35, v32, v33
	v_mul_f32_e32 v32, 0x4b800000, v40
	v_cndmask_b32_e32 v32, v40, v32, vcc
	v_rsq_f32_e32 v32, v32
	flat_store_dwordx2 v[20:21], v[34:35]
	v_and_b32_e32 v37, 0xffff0000, v17
	v_lshlrev_b32_e32 v36, 16, v17
	v_mul_f32_e32 v33, 0x45800000, v32
	v_cndmask_b32_e32 v32, v32, v33, vcc
	v_pk_mul_f32 v[30:31], v[30:31], v[32:33] op_sel_hi:[1,0]
	v_pk_mul_f32 v[32:33], v[44:45], v[32:33] op_sel_hi:[1,0]
	v_pk_mul_f32 v[28:29], v[28:29], v[30:31]
	v_mul_f32_e32 v30, 0xbfb8aa3b, v46
	v_mul_f32_e32 v31, 0xbfb8aa3b, v47
	v_exp_f32_e32 v30, v30
	v_exp_f32_e32 v31, v31
	v_cvt_pk_bf16_f32 v28, v28, v29
	v_and_b32_e32 v17, 0xffff0000, v16
	v_add_f32_e32 v30, 1.0, v30
	v_add_f32_e32 v31, 1.0, v31
	v_rcp_f32_e32 v30, v30
	v_rcp_f32_e32 v31, v31
	v_lshlrev_b32_e32 v16, 16, v16
	v_mul_f32_e32 v38, 0xbfb8aa3b, v16
	v_mul_f32_e32 v39, 0xbfb8aa3b, v17
	v_pk_mul_f32 v[30:31], v[30:31], v[46:47]
	v_exp_f32_e32 v38, v38
	v_pk_mul_f32 v[30:31], v[30:31], v[32:33]
	v_exp_f32_e32 v39, v39
	v_cvt_pk_bf16_f32 v29, v30, v31
	flat_store_dwordx2 v[20:21], v[28:29] offset:2048
	v_and_b32_e32 v29, 0xffff0000, v25
	v_lshlrev_b32_e32 v28, 16, v25
	v_and_b32_e32 v25, 0xffff0000, v24
	v_lshlrev_b32_e32 v24, 16, v24
	v_mul_f32_e32 v34, 0xbfb8aa3b, v28
	v_mul_f32_e32 v35, 0xbfb8aa3b, v29
	v_mul_f32_e32 v30, 0xbfb8aa3b, v24
	v_mul_f32_e32 v31, 0xbfb8aa3b, v25
	v_exp_f32_e32 v34, v34
	v_exp_f32_e32 v35, v35
	v_exp_f32_e32 v30, v30
	v_exp_f32_e32 v31, v31
	v_add_f32_e32 v34, 1.0, v34
	v_add_f32_e32 v35, 1.0, v35
	v_add_f32_e32 v30, 1.0, v30
	v_add_f32_e32 v31, 1.0, v31
	v_rcp_f32_e32 v34, v34
	v_rcp_f32_e32 v35, v35
	v_add_f32_e32 v38, 1.0, v38
	v_add_f32_e32 v39, 1.0, v39
	v_rcp_f32_e32 v30, v30
	v_rcp_f32_e32 v31, v31
	v_rcp_f32_e32 v38, v38
	v_rcp_f32_e32 v39, v39
	v_and_b32_e32 v21, 0xffff0000, v23
	v_lshlrev_b32_e32 v20, 16, v23
	v_and_b32_e32 v23, 0xffff0000, v22
	v_lshlrev_b32_e32 v22, 16, v22
	v_pk_mul_f32 v[28:29], v[34:35], v[28:29]
	v_and_b32_e32 v35, 0xffff0000, v19
	v_lshlrev_b32_e32 v34, 16, v19
	v_and_b32_e32 v19, 0xffff0000, v18
	v_lshlrev_b32_e32 v18, 16, v18
	v_pk_mul_f32 v[24:25], v[30:31], v[24:25]
	v_add_f32_e32 v30, v23, v22
	v_pk_mul_f32 v[16:17], v[38:39], v[16:17]
	v_add_f32_e32 v38, v19, v18
	v_add_f32_e32 v30, v30, v20
	v_add_f32_e32 v38, v38, v34
	v_add_f32_e32 v30, v30, v21
	v_add_f32_e32 v38, v38, v35
	s_nop 1
	v_add_f32_dpp v30, v30, v30 quad_perm:[1,0,3,2] row_mask:0xf bank_mask:0xf
	v_add_f32_dpp v38, v38, v38 quad_perm:[1,0,3,2] row_mask:0xf bank_mask:0xf
	s_nop 1
	v_add_f32_dpp v30, v30, v30 quad_perm:[2,3,0,1] row_mask:0xf bank_mask:0xf
	v_add_f32_dpp v38, v38, v38 quad_perm:[2,3,0,1] row_mask:0xf bank_mask:0xf
	s_nop 1
	v_add_f32_dpp v30, v30, v30 row_half_mirror row_mask:0xf bank_mask:0xf
	v_add_f32_dpp v38, v38, v38 row_half_mirror row_mask:0xf bank_mask:0xf
	s_nop 1
	v_add_f32_dpp v30, v30, v30 row_mirror row_mask:0xf bank_mask:0xf
	v_add_f32_dpp v38, v38, v38 row_mirror row_mask:0xf bank_mask:0xf
	v_mov_b32_e32 v31, v30
	v_mov_b32_e32 v39, v38
	s_nop 1
	v_permlane16_swap_b32_e32 v30, v31
	v_permlane16_swap_b32_e32 v38, v39
	v_add_f32_e32 v30, v30, v31
	v_add_f32_e32 v38, v38, v39
	v_mov_b32_e32 v31, v30
	v_mov_b32_e32 v39, v38
	s_nop 1
	v_permlane32_swap_b32_e32 v30, v31
	v_permlane32_swap_b32_e32 v38, v39
	v_add_f32_e32 v30, v30, v31
	v_add_f32_e32 v38, v38, v39
	v_mul_f32_e32 v30, 0x3b800000, v30
	v_mul_f32_e32 v38, 0x3b800000, v38
	v_pk_add_f32 v[22:23], v[22:23], v[30:31] op_sel_hi:[1,0] neg_lo:[0,1] neg_hi:[0,1]
	v_pk_add_f32 v[18:19], v[18:19], v[38:39] op_sel_hi:[1,0] neg_lo:[0,1] neg_hi:[0,1]
	v_pk_add_f32 v[20:21], v[20:21], v[30:31] op_sel_hi:[1,0] neg_lo:[0,1] neg_hi:[0,1]
	v_pk_mul_f32 v[30:31], v[22:23], v[22:23]
	v_pk_add_f32 v[34:35], v[34:35], v[38:39] op_sel_hi:[1,0] neg_lo:[0,1] neg_hi:[0,1]
	v_pk_mul_f32 v[38:39], v[18:19], v[18:19]
	v_pk_mul_f32 v[32:33], v[20:21], v[20:21]
	v_pk_mul_f32 v[40:41], v[34:35], v[34:35]
	v_mov_b32_e32 v42, v38
	v_mov_b32_e32 v43, v30
	v_mov_b32_e32 v30, v39
	v_pk_add_f32 v[30:31], v[42:43], v[30:31]
	v_mov_b32_e32 v38, v40
	v_mov_b32_e32 v39, v32
	v_pk_add_f32 v[30:31], v[38:39], v[30:31]
	v_mov_b32_e32 v32, v41
	v_pk_add_f32 v[30:31], v[32:33], v[30:31]
	s_nop 1
	v_add_f32_dpp v30, v30, v30 quad_perm:[1,0,3,2] row_mask:0xf bank_mask:0xf
	v_add_f32_dpp v31, v31, v31 quad_perm:[1,0,3,2] row_mask:0xf bank_mask:0xf
	s_nop 1
	v_add_f32_dpp v30, v30, v30 quad_perm:[2,3,0,1] row_mask:0xf bank_mask:0xf
	v_add_f32_dpp v31, v31, v31 quad_perm:[2,3,0,1] row_mask:0xf bank_mask:0xf
	s_nop 1
	v_add_f32_dpp v30, v30, v30 row_half_mirror row_mask:0xf bank_mask:0xf
	v_add_f32_dpp v31, v31, v31 row_half_mirror row_mask:0xf bank_mask:0xf
	s_nop 1
	v_add_f32_dpp v30, v30, v30 row_mirror row_mask:0xf bank_mask:0xf
	v_add_f32_dpp v31, v31, v31 row_mirror row_mask:0xf bank_mask:0xf
	v_mov_b32_e32 v32, v30
	v_mov_b32_e32 v33, v31
	s_nop 1
	v_permlane16_swap_b32_e32 v30, v32
	v_permlane16_swap_b32_e32 v31, v33
	v_add_f32_e32 v30, v30, v32
	v_add_f32_e32 v31, v31, v33
	v_mov_b32_e32 v32, v30
	v_mov_b32_e32 v33, v31
	s_nop 1
	v_permlane32_swap_b32_e32 v30, v32
	v_permlane32_swap_b32_e32 v31, v33
	v_add_f32_e32 v30, v30, v32
	v_add_f32_e32 v31, v31, v33
	s_nop 0
	v_pk_fma_f32 v[30:31], v[30:31], s[28:29], v[26:27] op_sel_hi:[1,0,0]
	s_nop 0
	v_mul_f32_e32 v32, 0x4b800000, v31
	v_cmp_gt_f32_e64 s[20:21], s39, v31
	v_cmp_gt_f32_e32 vcc, s39, v30
	s_nop 0
	v_cndmask_b32_e64 v31, v31, v32, s[20:21]
	v_rsq_f32_e32 v31, v31
	s_nop 0
	v_mul_f32_e32 v32, 0x45800000, v31
	v_cndmask_b32_e64 v32, v31, v32, s[20:21]
	v_pk_mul_f32 v[22:23], v[22:23], v[32:33] op_sel_hi:[1,0]
	v_pk_mul_f32 v[20:21], v[20:21], v[32:33] op_sel_hi:[1,0]
	v_pk_mul_f32 v[22:23], v[24:25], v[22:23]
	v_pk_mul_f32 v[20:21], v[28:29], v[20:21]
	v_cvt_pk_bf16_f32 v22, v22, v23
	v_cvt_pk_bf16_f32 v23, v20, v21
	v_mul_f32_e32 v20, 0x4b800000, v30
	v_cndmask_b32_e32 v20, v30, v20, vcc
	v_rsq_f32_e32 v20, v20
	flat_store_dwordx2 v[10:11], v[22:23]
	v_and_b32_e32 v25, 0xffff0000, v7
	v_lshlrev_b32_e32 v24, 16, v7
	v_mul_f32_e32 v21, 0x45800000, v20
	v_cndmask_b32_e32 v20, v20, v21, vcc
	v_pk_mul_f32 v[18:19], v[18:19], v[20:21] op_sel_hi:[1,0]
	v_pk_mul_f32 v[20:21], v[34:35], v[20:21] op_sel_hi:[1,0]
	v_pk_mul_f32 v[16:17], v[16:17], v[18:19]
	v_mul_f32_e32 v18, 0xbfb8aa3b, v36
	v_mul_f32_e32 v19, 0xbfb8aa3b, v37
	v_exp_f32_e32 v18, v18
	v_exp_f32_e32 v19, v19
	v_cvt_pk_bf16_f32 v16, v16, v17
	v_and_b32_e32 v7, 0xffff0000, v6
	v_add_f32_e32 v18, 1.0, v18
	v_add_f32_e32 v19, 1.0, v19
	v_rcp_f32_e32 v18, v18
	v_rcp_f32_e32 v19, v19
	v_lshlrev_b32_e32 v6, 16, v6
	v_mul_f32_e32 v28, 0xbfb8aa3b, v6
	v_mul_f32_e32 v29, 0xbfb8aa3b, v7
	v_pk_mul_f32 v[18:19], v[18:19], v[36:37]
	v_exp_f32_e32 v28, v28
	v_pk_mul_f32 v[18:19], v[18:19], v[20:21]
	v_exp_f32_e32 v29, v29
	v_cvt_pk_bf16_f32 v17, v18, v19
	flat_store_dwordx2 v[10:11], v[16:17] offset:2048
	v_and_b32_e32 v17, 0xffff0000, v15
	v_lshlrev_b32_e32 v16, 16, v15
	v_and_b32_e32 v15, 0xffff0000, v14
	v_lshlrev_b32_e32 v14, 16, v14
	v_mul_f32_e32 v22, 0xbfb8aa3b, v16
	v_mul_f32_e32 v23, 0xbfb8aa3b, v17
	v_mul_f32_e32 v18, 0xbfb8aa3b, v14
	v_mul_f32_e32 v19, 0xbfb8aa3b, v15
	v_exp_f32_e32 v22, v22
	v_exp_f32_e32 v23, v23
	v_exp_f32_e32 v18, v18
	v_exp_f32_e32 v19, v19
	v_add_f32_e32 v22, 1.0, v22
	v_add_f32_e32 v23, 1.0, v23
	v_add_f32_e32 v18, 1.0, v18
	v_add_f32_e32 v19, 1.0, v19
	v_rcp_f32_e32 v22, v22
	v_rcp_f32_e32 v23, v23
	v_add_f32_e32 v28, 1.0, v28
	v_add_f32_e32 v29, 1.0, v29
	v_rcp_f32_e32 v18, v18
	v_rcp_f32_e32 v19, v19
	v_rcp_f32_e32 v28, v28
	v_rcp_f32_e32 v29, v29
	v_and_b32_e32 v11, 0xffff0000, v13
	v_lshlrev_b32_e32 v10, 16, v13
	v_and_b32_e32 v13, 0xffff0000, v12
	v_lshlrev_b32_e32 v12, 16, v12
	v_pk_mul_f32 v[16:17], v[22:23], v[16:17]
	v_and_b32_e32 v23, 0xffff0000, v9
	v_lshlrev_b32_e32 v22, 16, v9
	v_and_b32_e32 v9, 0xffff0000, v8
	v_lshlrev_b32_e32 v8, 16, v8
	v_pk_mul_f32 v[14:15], v[18:19], v[14:15]
	v_add_f32_e32 v18, v13, v12
	v_pk_mul_f32 v[6:7], v[28:29], v[6:7]
	v_add_f32_e32 v28, v9, v8
	v_add_f32_e32 v18, v18, v10
	v_add_f32_e32 v28, v28, v22
	v_add_f32_e32 v18, v18, v11
	v_add_f32_e32 v28, v28, v23
	s_nop 1
	v_add_f32_dpp v18, v18, v18 quad_perm:[1,0,3,2] row_mask:0xf bank_mask:0xf
	v_add_f32_dpp v28, v28, v28 quad_perm:[1,0,3,2] row_mask:0xf bank_mask:0xf
	s_nop 1
	v_add_f32_dpp v18, v18, v18 quad_perm:[2,3,0,1] row_mask:0xf bank_mask:0xf
	v_add_f32_dpp v28, v28, v28 quad_perm:[2,3,0,1] row_mask:0xf bank_mask:0xf
	s_nop 1
	v_add_f32_dpp v18, v18, v18 row_half_mirror row_mask:0xf bank_mask:0xf
	v_add_f32_dpp v28, v28, v28 row_half_mirror row_mask:0xf bank_mask:0xf
	s_nop 1
	v_add_f32_dpp v18, v18, v18 row_mirror row_mask:0xf bank_mask:0xf
	v_add_f32_dpp v28, v28, v28 row_mirror row_mask:0xf bank_mask:0xf
	v_mov_b32_e32 v19, v18
	v_mov_b32_e32 v29, v28
	s_nop 1
	v_permlane16_swap_b32_e32 v18, v19
	v_permlane16_swap_b32_e32 v28, v29
	v_add_f32_e32 v18, v18, v19
	v_add_f32_e32 v28, v28, v29
	v_mov_b32_e32 v19, v18
	v_mov_b32_e32 v29, v28
	s_nop 1
	v_permlane32_swap_b32_e32 v18, v19
	v_permlane32_swap_b32_e32 v28, v29
	v_add_f32_e32 v18, v18, v19
	v_add_f32_e32 v28, v28, v29
	v_mul_f32_e32 v18, 0x3b800000, v18
	v_mul_f32_e32 v28, 0x3b800000, v28
	v_pk_add_f32 v[12:13], v[12:13], v[18:19] op_sel_hi:[1,0] neg_lo:[0,1] neg_hi:[0,1]
	v_pk_add_f32 v[8:9], v[8:9], v[28:29] op_sel_hi:[1,0] neg_lo:[0,1] neg_hi:[0,1]
	v_pk_add_f32 v[10:11], v[10:11], v[18:19] op_sel_hi:[1,0] neg_lo:[0,1] neg_hi:[0,1]
	v_pk_mul_f32 v[18:19], v[12:13], v[12:13]
	v_pk_add_f32 v[22:23], v[22:23], v[28:29] op_sel_hi:[1,0] neg_lo:[0,1] neg_hi:[0,1]
	v_pk_mul_f32 v[28:29], v[8:9], v[8:9]
	v_pk_mul_f32 v[20:21], v[10:11], v[10:11]
	v_pk_mul_f32 v[30:31], v[22:23], v[22:23]
	v_mov_b32_e32 v32, v28
	v_mov_b32_e32 v33, v18
	v_mov_b32_e32 v18, v29
	v_pk_add_f32 v[18:19], v[32:33], v[18:19]
	v_mov_b32_e32 v28, v30
	v_mov_b32_e32 v29, v20
	v_pk_add_f32 v[18:19], v[28:29], v[18:19]
	v_mov_b32_e32 v20, v31
	v_pk_add_f32 v[18:19], v[20:21], v[18:19]
	s_nop 1
	v_add_f32_dpp v18, v18, v18 quad_perm:[1,0,3,2] row_mask:0xf bank_mask:0xf
	v_add_f32_dpp v19, v19, v19 quad_perm:[1,0,3,2] row_mask:0xf bank_mask:0xf
	s_nop 1
	v_add_f32_dpp v18, v18, v18 quad_perm:[2,3,0,1] row_mask:0xf bank_mask:0xf
	v_add_f32_dpp v19, v19, v19 quad_perm:[2,3,0,1] row_mask:0xf bank_mask:0xf
	s_nop 1
	v_add_f32_dpp v18, v18, v18 row_half_mirror row_mask:0xf bank_mask:0xf
	v_add_f32_dpp v19, v19, v19 row_half_mirror row_mask:0xf bank_mask:0xf
	s_nop 1
	v_add_f32_dpp v18, v18, v18 row_mirror row_mask:0xf bank_mask:0xf
	v_add_f32_dpp v19, v19, v19 row_mirror row_mask:0xf bank_mask:0xf
	v_mov_b32_e32 v20, v18
	v_mov_b32_e32 v21, v19
	s_nop 1
	v_permlane16_swap_b32_e32 v18, v20
	v_permlane16_swap_b32_e32 v19, v21
	v_add_f32_e32 v18, v18, v20
	v_add_f32_e32 v19, v19, v21
	v_mov_b32_e32 v20, v18
	v_mov_b32_e32 v21, v19
	s_nop 1
	v_permlane32_swap_b32_e32 v18, v20
	v_permlane32_swap_b32_e32 v19, v21
	v_add_f32_e32 v18, v18, v20
	v_add_f32_e32 v19, v19, v21
	s_nop 0
	v_pk_fma_f32 v[18:19], v[18:19], s[28:29], v[26:27] op_sel_hi:[1,0,0]
	s_nop 0
	v_mul_f32_e32 v20, 0x4b800000, v19
	v_cmp_gt_f32_e64 s[20:21], s39, v19
	v_cmp_gt_f32_e32 vcc, s39, v18
	s_nop 0
	v_cndmask_b32_e64 v19, v19, v20, s[20:21]
	v_rsq_f32_e32 v19, v19
	s_nop 0
	v_mul_f32_e32 v20, 0x45800000, v19
	v_cndmask_b32_e64 v20, v19, v20, s[20:21]
	v_pk_mul_f32 v[12:13], v[12:13], v[20:21] op_sel_hi:[1,0]
	v_pk_mul_f32 v[10:11], v[10:11], v[20:21] op_sel_hi:[1,0]
	v_pk_mul_f32 v[12:13], v[14:15], v[12:13]
	v_pk_mul_f32 v[10:11], v[16:17], v[10:11]
	v_cvt_pk_bf16_f32 v12, v12, v13
	v_cvt_pk_bf16_f32 v13, v10, v11
	v_mul_f32_e32 v10, 0x4b800000, v18
	v_cndmask_b32_e32 v10, v18, v10, vcc
	v_rsq_f32_e32 v10, v10
	flat_store_dwordx2 v[4:5], v[12:13]
	v_mul_f32_e32 v11, 0x45800000, v10
	v_cndmask_b32_e32 v10, v10, v11, vcc
	v_pk_mul_f32 v[8:9], v[8:9], v[10:11] op_sel_hi:[1,0]
	v_pk_mul_f32 v[10:11], v[22:23], v[10:11] op_sel_hi:[1,0]
	v_pk_mul_f32 v[6:7], v[6:7], v[8:9]
	v_mul_f32_e32 v8, 0xbfb8aa3b, v24
	v_mul_f32_e32 v9, 0xbfb8aa3b, v25
	v_exp_f32_e32 v8, v8
	v_exp_f32_e32 v9, v9
	v_cvt_pk_bf16_f32 v6, v6, v7
	v_add_f32_e32 v8, 1.0, v8
	v_add_f32_e32 v9, 1.0, v9
	v_rcp_f32_e32 v8, v8
	v_rcp_f32_e32 v9, v9
	s_nop 0
	v_pk_mul_f32 v[8:9], v[8:9], v[24:25]
	s_nop 0
	v_pk_mul_f32 v[8:9], v[8:9], v[10:11]
	s_nop 0
	v_cvt_pk_bf16_f32 v7, v8, v9
	flat_store_dwordx2 v[4:5], v[6:7] offset:2048
	s_cbranch_scc1 .LBB0_744
	v_add_u32_e32 v71, s33, v71
	s_movk_i32 s20, 0x3ff
	v_cmp_lt_i32_e32 vcc, s20, v71
	s_or_b64 s[26:27], vcc, s[26:27]
	v_add_u16_e32 v213, s33, v213
	s_andn2_b64 exec, exec, s[26:27]
	s_cbranch_execnz .LBB0_509
